# DSA score loop: 32 redundant canonicalising v_max x,x,x before the relu max replaced by s_nop 0 (value-identical)
# speedup vs baseline: 1.0136x; 1.0136x over previous
.LBB0_193:
	v_mfma_f32_32x32x16_bf16 v[18:33], v[34:37], v[2:5], 0
	s_mov_b64 s[42:43], 0x4000
	v_lshl_add_u64 v[126:127], v[126:127], 0, s[42:43]
	v_mfma_f32_32x32x16_bf16 v[18:33], v[38:41], v[122:125], v[18:33]
	v_mfma_f32_32x32x16_bf16 v[2:17], v[50:53], v[2:5], 0
	v_mfma_f32_32x32x16_bf16 v[18:33], v[42:45], v[118:121], v[18:33]
	v_mfma_f32_32x32x16_bf16 v[2:17], v[54:57], v[122:125], v[2:17]
	s_waitcnt vmcnt(2)
	v_mov_b64_e32 v[124:125], v[108:109]
	v_mov_b64_e32 v[122:123], v[106:107]
	v_mfma_f32_32x32x16_bf16 v[18:33], v[46:49], v[114:117], v[18:33]
	s_waitcnt vmcnt(1)
	v_mfma_f32_32x32x16_bf16 v[2:17], v[90:93], v[118:121], v[2:17]
	s_nop 9
	s_nop 0
	s_nop 0
	s_nop 0
	s_nop 0
	v_max_f32_e32 v18, 0, v18
	v_max_f32_e32 v26, 0, v26
	v_max_f32_e32 v19, 0, v19
	v_max_f32_e32 v27, 0, v27
	v_pk_mul_f32 v[18:19], v[70:71], v[18:19]
	v_pk_mul_f32 v[26:27], v[62:63], v[26:27]
	s_nop 0
	s_nop 0
	s_nop 0
	s_nop 0
	s_waitcnt vmcnt(0)
	v_mfma_f32_32x32x16_bf16 v[2:17], v[94:97], v[114:117], v[2:17]
	v_max_f32_e32 v20, 0, v20
	v_max_f32_e32 v28, 0, v28
	v_max_f32_e32 v21, 0, v21
	v_max_f32_e32 v29, 0, v29
	v_mov_b32_e32 v114, v26
	v_mov_b32_e32 v115, v18
	v_pk_mul_f32 v[20:21], v[72:73], v[20:21]
	v_pk_mul_f32 v[28:29], v[64:65], v[28:29]
	s_nop 0
	s_nop 0
	s_nop 0
	s_nop 0
	v_pk_add_f32 v[114:115], v[114:115], 0 op_sel_hi:[1,0]
	v_mov_b32_e32 v18, v27
	v_max_f32_e32 v22, 0, v22
	v_max_f32_e32 v30, 0, v30
	v_max_f32_e32 v23, 0, v23
	v_max_f32_e32 v31, 0, v31
	v_pk_add_f32 v[18:19], v[18:19], v[114:115]
	v_mov_b32_e32 v26, v28
	v_mov_b32_e32 v27, v20
	v_pk_mul_f32 v[22:23], v[66:67], v[22:23]
	v_pk_mul_f32 v[30:31], v[58:59], v[30:31]
	s_nop 0
	s_nop 0
	s_nop 0
	s_nop 0
	v_pk_add_f32 v[18:19], v[26:27], v[18:19]
	v_mov_b32_e32 v20, v29
	v_max_f32_e32 v24, 0, v24
	v_max_f32_e32 v32, 0, v32
	v_max_f32_e32 v25, 0, v25
	v_max_f32_e32 v33, 0, v33
	v_pk_add_f32 v[18:19], v[20:21], v[18:19]
	v_mov_b32_e32 v20, v30
	v_mov_b32_e32 v21, v22
	v_pk_mul_f32 v[24:25], v[68:69], v[24:25]
	v_pk_mul_f32 v[32:33], v[60:61], v[32:33]
	v_pk_add_f32 v[18:19], v[20:21], v[18:19]
	v_mov_b32_e32 v22, v31
	v_pk_add_f32 v[18:19], v[22:23], v[18:19]
	v_mov_b32_e32 v20, v32
	v_mov_b32_e32 v21, v24
	v_pk_add_f32 v[18:19], v[20:21], v[18:19]
	v_mov_b32_e32 v24, v33
	v_pk_add_f32 v[18:19], v[24:25], v[18:19]
	s_nop 0
	v_pk_add_f32 v[18:19], v[18:19], 0 op_sel_hi:[1,0]
	s_nop 0
	v_bfe_u32 v20, v19, 13, 18
	v_med3_u32 v20, v20, s44, v197
	v_add_u32_e32 v21, 0x5400, v20
	v_sub_u32_e32 v20, 0x22bff, v20
	v_or_b32_e32 v21, 0x8000, v21
	v_max_u32_e32 v20, 1, v20
	v_cmp_gt_i32_e32 vcc, 0, v19
	s_nop 0
	s_nop 0
	v_cndmask_b32_e32 v19, v21, v20, vcc
	v_cmp_le_u32_e32 vcc, v133, v128
	v_max_f32_e32 v2, 0, v2
	v_max_f32_e32 v10, 0, v10
	v_cndmask_b32_e32 v19, 0, v19, vcc
	ds_write_b16 v132, v19
	v_bfe_u32 v19, v18, 13, 18
	v_med3_u32 v19, v19, s44, v197
	v_add_u32_e32 v20, 0x5400, v19
	v_sub_u32_e32 v19, 0x22bff, v19
	v_or_b32_e32 v20, 0x8000, v20
	v_max_u32_e32 v19, 1, v19
	v_cmp_gt_i32_e32 vcc, 0, v18
	v_max_f32_e32 v3, 0, v3
	v_max_f32_e32 v11, 0, v11
	v_cndmask_b32_e32 v18, v20, v19, vcc
	v_cmp_le_u32_e32 vcc, v133, v129
	v_pk_mul_f32 v[2:3], v[86:87], v[2:3]
	v_pk_mul_f32 v[10:11], v[78:79], v[10:11]
	s_nop 0
	s_nop 0
	s_nop 0
	s_nop 0
	v_cndmask_b32_e32 v18, 0, v18, vcc
	v_max_f32_e32 v4, 0, v4
	v_max_f32_e32 v12, 0, v12
	v_max_f32_e32 v5, 0, v5
	v_max_f32_e32 v13, 0, v13
	ds_write_b16 v132, v18 offset:8192
	v_mov_b32_e32 v18, v10
	v_mov_b32_e32 v19, v2
	v_pk_mul_f32 v[4:5], v[88:89], v[4:5]
	v_pk_mul_f32 v[12:13], v[80:81], v[12:13]
	s_nop 0
	s_nop 0
	s_nop 0
	s_nop 0
	v_pk_add_f32 v[18:19], v[18:19], 0 op_sel_hi:[1,0]
	v_mov_b32_e32 v2, v11
	v_max_f32_e32 v6, 0, v6
	v_max_f32_e32 v14, 0, v14
	v_max_f32_e32 v7, 0, v7
	v_max_f32_e32 v15, 0, v15
	v_pk_add_f32 v[2:3], v[2:3], v[18:19]
	v_mov_b32_e32 v10, v12
	v_mov_b32_e32 v11, v4
	v_pk_mul_f32 v[6:7], v[82:83], v[6:7]
	v_pk_mul_f32 v[14:15], v[74:75], v[14:15]
	s_nop 0
	s_nop 0
	s_nop 0
	s_nop 0
	v_pk_add_f32 v[2:3], v[10:11], v[2:3]
	v_mov_b32_e32 v4, v13
	v_max_f32_e32 v8, 0, v8
	v_max_f32_e32 v16, 0, v16
	v_max_f32_e32 v9, 0, v9
	v_max_f32_e32 v17, 0, v17
	v_pk_add_f32 v[2:3], v[4:5], v[2:3]
	v_mov_b32_e32 v4, v14
	v_mov_b32_e32 v5, v6
	v_pk_mul_f32 v[8:9], v[84:85], v[8:9]
	v_pk_mul_f32 v[16:17], v[76:77], v[16:17]
	v_pk_add_f32 v[2:3], v[4:5], v[2:3]
	v_mov_b32_e32 v6, v15
	v_pk_add_f32 v[2:3], v[6:7], v[2:3]
	v_mov_b32_e32 v4, v16
	v_mov_b32_e32 v5, v8
	v_pk_add_f32 v[2:3], v[4:5], v[2:3]
	v_mov_b32_e32 v8, v17
	v_pk_add_f32 v[2:3], v[8:9], v[2:3]
	v_mov_b64_e32 v[120:121], v[104:105]
	v_pk_add_f32 v[2:3], v[2:3], 0 op_sel_hi:[1,0]
	v_mov_b64_e32 v[116:117], v[100:101]
	v_bfe_u32 v4, v3, 13, 18
	v_med3_u32 v4, v4, s44, v197
	v_add_u32_e32 v5, 0x5400, v4
	v_sub_u32_e32 v4, 0x22bff, v4
	v_or_b32_e32 v5, 0x8000, v5
	v_max_u32_e32 v4, 1, v4
	v_cmp_gt_i32_e32 vcc, 0, v3
	v_mov_b64_e32 v[118:119], v[102:103]
	v_mov_b64_e32 v[114:115], v[98:99]
	v_cndmask_b32_e32 v3, v5, v4, vcc
	v_cmp_le_u32_e32 vcc, v133, v130
	s_nop 1
	v_cndmask_b32_e32 v3, 0, v3, vcc
	ds_write_b16 v132, v3 offset:32768
	v_bfe_u32 v3, v2, 13, 18
	v_med3_u32 v3, v3, s44, v197
	v_add_u32_e32 v4, 0x5400, v3
	v_sub_u32_e32 v3, 0x22bff, v3
	v_or_b32_e32 v4, 0x8000, v4
	v_max_u32_e32 v3, 1, v3
	v_cmp_gt_i32_e32 vcc, 0, v2
	s_nop 1
	v_cndmask_b32_e32 v2, v4, v3, vcc
	v_cmp_le_u32_e32 vcc, v133, v131
	v_add_u32_e32 v133, 0x80, v133
	s_nop 0
	v_cndmask_b32_e32 v2, 0, v2, vcc
	ds_write_b16 v132, v2 offset:40960
	v_mov_b64_e32 v[2:3], v[110:111]
	v_add_u32_e32 v132, 0x100, v132
	s_andn2_b64 vcc, exec, s[28:29]
	v_mov_b64_e32 v[4:5], v[112:113]
	s_cbranch_vccz .LBB0_196
